# LayerNorm loops: loop-invariant gamma/beta loads hoisted out of the row loop (only the per-batch scale/shift reloaded per row)
# speedup vs baseline: 1.0077x; 1.0077x over previous
; DI int tidx() { int t = __builtin_amdgcn_workitem_id_x(); asm volatile("" : "+v"(t)); return t; }
; DI void phase_ln(const Params& p, const float* g, const float* bta, const float* sh, const float* sc, bool writex, int bid, int nb) {
;   const int tid = tidx(), lane = tid & 63, wid = tid >> 6;
;   for (int row = bid * 8 + wid; row < NTOK; row += nb * 8) {
;     float* xr = p.out + (size_t)row * DM; const int b = row >> 12;
;     f32x4 v[4]; float s = 0.f;
; #pragma unroll
;     for (int e = 0; e < 4; ++e) { v[e] = *(const f32x4*)(xr + e * 256 + lane * 4); s += (v[e][0] + v[e][1]) + (v[e][2] + v[e][3]); }
; #pragma unroll
;     for (int o = 32; o > 0; o >>= 1) s += __shfl_xor(s, o);
;     const float mu = s * (1.f / 1024.f); float q = 0.f;
; #pragma unroll
;     for (int e = 0; e < 4; ++e) { v[e] -= mu; q += (v[e][0] * v[e][0] + v[e][1] * v[e][1]) + (v[e][2] * v[e][2] + v[e][3] * v[e][3]); }
; #pragma unroll
;     for (int o = 32; o > 0; o >>= 1) q += __shfl_xor(q, o);
;     const float rstd = rsqrtf(q * (1.f / 1024.f) + 1e-5f);
;     if (!writex && lane == 0) { f32x2 ms = {mu, rstd}; *(f32x2*)(p.lnstat + (size_t)row * 2) = ms; }
; #pragma unroll
;     for (int e = 0; e < 4; ++e) { const int col = e * 256 + lane * 4;
;       const f32x4 y = v[e] * rstd * *(const f32x4*)(g + col) + *(const f32x4*)(bta + col);
.LBB0_779:
	s_or_b64 exec, exec, s[0:1]
	s_lshl_b32 s4, s79, 3
	v_mov_b32_e32 v1, v206
	s_mov_b32 s0, s4
	s_waitcnt lgkmcnt(0)
	s_barrier
	v_writelane_b32 v255, s0, 3
	v_ashrrev_i32_e32 v0, 6, v1
	v_add_u32_e32 v31, s4, v0
	v_writelane_b32 v255, s1, 4
	s_mov_b32 s0, 0x8000
	v_cmp_gt_i32_e32 vcc, s0, v31
	s_and_saveexec_b64 s[4:5], vcc
	s_cbranch_execz .LBB0_784
	v_cmp_lt_i32_e64 s[0:1], v209, v208
	v_and_b32_e32 v6, 63, v1
	v_readlane_b32 s8, v252, 60
	v_cndmask_b32_e64 v1, v207, v209, s[0:1]
	v_lshlrev_b32_e32 v32, 2, v1
	v_xor_b32_e32 v1, 16, v207
	v_cmp_lt_i32_e64 s[0:1], v1, v208
	v_readlane_b32 s9, v252, 61
	v_readlane_b32 s10, v252, 62
	v_cndmask_b32_e64 v1, v207, v1, s[0:1]
	v_lshlrev_b32_e32 v33, 2, v1
	v_xor_b32_e32 v1, 8, v207
	v_cmp_lt_i32_e64 s[0:1], v1, v208
	v_readlane_b32 s11, v252, 63
	v_readlane_b32 s12, v251, 0
	v_cndmask_b32_e64 v1, v207, v1, s[0:1]
	v_lshlrev_b32_e32 v34, 2, v1
	v_xor_b32_e32 v1, 4, v207
	v_cmp_lt_i32_e64 s[0:1], v1, v208
	v_readlane_b32 s13, v251, 1
	v_readlane_b32 s14, v251, 2
	v_cndmask_b32_e64 v1, v207, v1, s[0:1]
	v_lshlrev_b32_e32 v35, 2, v1
	v_xor_b32_e32 v1, 2, v207
	v_readlane_b32 s15, v251, 3
	v_readlane_b32 s16, v251, 4
	v_readlane_b32 s17, v251, 5
	v_cmp_lt_i32_e64 s[0:1], v1, v208
	v_readlane_b32 s18, v251, 6
	v_readlane_b32 s19, v251, 7
	v_readlane_b32 s20, v251, 8
	v_readlane_b32 s21, v251, 9
	v_readlane_b32 s22, v251, 10
	v_readlane_b32 s23, v251, 11
	s_mov_b64 s[8:9], s[16:17]
	v_cndmask_b32_e64 v1, v207, v1, s[0:1]
	v_lshlrev_b32_e32 v2, 4, v6
	v_mov_b32_e32 v3, 0
	s_mov_b64 s[10:11], s[18:19]
	s_mov_b64 s[12:13], s[20:21]
	s_mov_b64 s[14:15], s[22:23]
	v_lshlrev_b32_e32 v36, 2, v1
	v_xor_b32_e32 v1, 1, v207
	v_lshl_add_u64 v[16:17], s[12:13], 0, v[2:3]
	v_lshl_add_u64 v[18:19], s[14:15], 0, v[2:3]
	v_readlane_b32 s8, v252, 17
	v_cmp_lt_i32_e64 s[0:1], v1, v208
	v_readlane_b32 s16, v252, 25
	v_readlane_b32 s17, v252, 26
	v_cndmask_b32_e64 v1, v207, v1, s[0:1]
	s_mov_b64 s[0:1], 0x4000
	v_lshl_add_u64 v[4:5], s[16:17], 0, v[2:3]
	v_lshl_add_u64 v[20:21], v[4:5], 0, s[0:1]
	s_mov_b64 s[0:1], 0x3000
	v_readlane_b32 s9, v252, 18
	v_lshl_add_u64 v[22:23], v[4:5], 0, s[0:1]
	v_readlane_b32 s0, v255, 3
	v_lshlrev_b32_e32 v37, 2, v1
	v_readlane_b32 s10, v252, 19
	v_readlane_b32 s11, v252, 20
	v_readlane_b32 s12, v252, 21
	v_readlane_b32 s13, v252, 22
	v_readlane_b32 s14, v252, 23
	v_readlane_b32 s15, v252, 24
	v_readlane_b32 s18, v252, 27
	v_readlane_b32 s19, v252, 28
	v_readlane_b32 s20, v252, 29
	v_readlane_b32 s21, v252, 30
	v_readlane_b32 s22, v252, 31
	v_readlane_b32 s23, v252, 32
	v_ashrrev_i32_e32 v1, 31, v0
	s_mov_b32 s8, s0
	s_ashr_i32 s9, s0, 31
	v_lshl_add_u64 v[0:1], v[0:1], 0, s[8:9]
	v_readlane_b32 s8, v252, 0
	v_readlane_b32 s1, v255, 4
	v_readlane_b32 s9, v252, 1
	v_lshlrev_b64 v[4:5], 12, v[0:1]
	v_writelane_b32 v255, s0, 3
	v_lshl_add_u64 v[24:25], v[0:1], 3, s[8:9]
	v_or_b32_e32 v4, v4, v2
	v_lshlrev_b64 v[0:1], 11, v[0:1]
	s_lshl_b32 s6, s38, 3
	v_writelane_b32 v255, s1, 4
	v_readlane_b32 s14, v252, 6
	v_readlane_b32 s15, v252, 7
	v_lshl_add_u64 v[2:3], s[84:85], 0, v[4:5]
	s_mov_b64 s[0:1], 0x800
	v_lshl_or_b32 v0, v6, 3, v0
	v_readlane_b32 s10, v252, 2
	v_readlane_b32 s11, v252, 3
	v_readlane_b32 s12, v252, 4
	v_readlane_b32 s13, v252, 5
	s_ashr_i32 s7, s6, 31
	v_lshl_add_u64 v[26:27], v[2:3], 0, s[0:1]
	v_lshl_add_u64 v[0:1], s[14:15], 0, v[0:1]
	s_mov_b64 s[0:1], 0x400
	v_cmp_eq_u32_e32 vcc, 0, v6
	s_lshl_b64 s[8:9], s[6:7], 3
	s_lshl_b64 s[10:11], s[6:7], 12
	v_lshl_add_u64 v[28:29], v[0:1], 0, s[0:1]
	s_lshl_b64 s[12:13], s[6:7], 11
	s_mov_b64 s[14:15], 0
	v_mov_b32_e32 v38, 0x3727c5ac
	v_readlane_b32 s16, v252, 8
	v_readlane_b32 s17, v252, 9
	v_readlane_b32 s18, v252, 10
	v_readlane_b32 s19, v252, 11
	v_readlane_b32 s20, v252, 12
	v_readlane_b32 s21, v252, 13
	v_readlane_b32 s22, v252, 14
	v_readlane_b32 s23, v252, 15
	global_load_dwordx4 v[52:55], v[16:17], off
	global_load_dwordx4 v[68:71], v[18:19], off
	global_load_dwordx4 v[56:59], v[16:17], off offset:1024
	global_load_dwordx4 v[72:75], v[18:19], off offset:1024
	global_load_dwordx4 v[60:63], v[16:17], off offset:2048
	global_load_dwordx4 v[76:79], v[18:19], off offset:2048
	global_load_dwordx4 v[64:67], v[16:17], off offset:3072
	global_load_dwordx4 v[80:83], v[18:19], off offset:3072
	global_load_dwordx4 v[124:127], v[26:27], off offset:-2048
	global_load_dwordx4 v[128:131], v[26:27], off offset:-1024
	global_load_dwordx4 v[132:135], v[26:27], off
	global_load_dwordx4 v[136:139], v[26:27], off offset:1024
	s_waitcnt vmcnt(0)
	s_branch .LBB0_782

; DI void st4(bf16_t* p, float a, float b, float c, float d) { u32x2 w = {pk2(a, b), pk2(c, d)}; *(u32x2*)p = w; }
; DI void phase_ln(const Params& p, const float* g, const float* bta, const float* sh, const float* sc, bool writex, int bid, int nb) {
;     ...
;   for (int row = bid * 8 + wid; row < NTOK; row += nb * 8) {
;     float* xr = p.out + (size_t)row * DM; const int b = row >> 12;
;     f32x4 v[4]; float s = 0.f;
; #pragma unroll
;     for (int e = 0; e < 4; ++e) { v[e] = *(const f32x4*)(xr + e * 256 + lane * 4); s += (v[e][0] + v[e][1]) + (v[e][2] + v[e][3]); }
; #pragma unroll
;     for (int o = 32; o > 0; o >>= 1) s += __shfl_xor(s, o);
;     const float mu = s * (1.f / 1024.f); float q = 0.f;
; #pragma unroll
;     for (int e = 0; e < 4; ++e) { v[e] -= mu; q += (v[e][0] * v[e][0] + v[e][1] * v[e][1]) + (v[e][2] * v[e][2] + v[e][3] * v[e][3]); }
; #pragma unroll
;     for (int o = 32; o > 0; o >>= 1) q += __shfl_xor(q, o);
;     const float rstd = rsqrtf(q * (1.f / 1024.f) + 1e-5f);
;     if (!writex && lane == 0) { f32x2 ms = {mu, rstd}; *(f32x2*)(p.lnstat + (size_t)row * 2) = ms; }
; #pragma unroll
;     for (int e = 0; e < 4; ++e) { const int col = e * 256 + lane * 4;
;       const f32x4 y = v[e] * rstd * *(const f32x4*)(g + col) + *(const f32x4*)(bta + col);
;       if (writex) *(f32x4*)(xr + col) = y;
;       if (sh) { const f32x4 hv = y * (*(const f32x4*)(sc + b * 6144 + col) + 1.f) + *(const f32x4*)(sh + b * 6144 + col); st4(p.H + (size_t)row * DM + col, hv[0], hv[1], hv[2], hv[3]); } }
.LBB0_782:
	s_waitcnt vmcnt(5)
	v_mov_b64_e32 v[12:13], v[124:125]
	v_mov_b64_e32 v[14:15], v[126:127]
	v_mov_b64_e32 v[8:9], v[128:129]
	v_mov_b64_e32 v[10:11], v[130:131]
	v_mov_b64_e32 v[4:5], v[132:133]
	v_mov_b64_e32 v[6:7], v[134:135]
	v_mov_b64_e32 v[0:1], v[136:137]
	v_mov_b64_e32 v[2:3], v[138:139]
	v_ashrrev_i32_e32 v116, 12, v31
	v_mul_i32_i24_e32 v116, 0x1800, v116
	v_ashrrev_i32_e32 v117, 31, v116
	v_lshlrev_b64 v[116:117], 2, v[116:117]
	v_lshl_add_u64 v[118:119], v[20:21], 0, v[116:117]
	v_lshl_add_u64 v[116:117], v[22:23], 0, v[116:117]
	global_load_dwordx4 v[84:87], v[118:119], off
	global_load_dwordx4 v[100:103], v[116:117], off
	global_load_dwordx4 v[88:91], v[118:119], off offset:1024
	global_load_dwordx4 v[104:107], v[116:117], off offset:1024
	global_load_dwordx4 v[92:95], v[118:119], off offset:2048
	global_load_dwordx4 v[108:111], v[116:117], off offset:2048
	global_load_dwordx4 v[96:99], v[118:119], off offset:3072
	global_load_dwordx4 v[112:115], v[116:117], off offset:3072
	v_add_u32_e32 v140, s6, v31
	s_movk_i32 s100, 0x7fff
	v_cmp_ge_i32_e64 s[98:99], s100, v140
	v_lshl_add_u64 v[142:143], v[26:27], 0, s[10:11]
	s_nop 1
	v_cndmask_b32_e64 v142, v26, v142, s[98:99]
	v_cndmask_b32_e64 v143, v27, v143, s[98:99]
	global_load_dwordx4 v[124:127], v[142:143], off offset:-2048
	global_load_dwordx4 v[128:131], v[142:143], off offset:-1024
	global_load_dwordx4 v[132:135], v[142:143], off
	global_load_dwordx4 v[136:139], v[142:143], off offset:1024
	s_mov_b32 s0, 0x800000
	v_mov_b32_e32 v120, v13
	v_mov_b32_e32 v121, v14
	v_mov_b32_e32 v122, v12
	v_mov_b32_e32 v123, v15
	v_pk_add_f32 v[120:121], v[120:121], v[122:123]
	v_mov_b32_e32 v122, v8
	v_add_f32_e32 v120, v120, v121
	v_add_f32_e32 v40, 0, v120
	v_mov_b32_e32 v120, v9
	v_mov_b32_e32 v121, v10
	v_mov_b32_e32 v123, v11
	v_pk_add_f32 v[120:121], v[120:121], v[122:123]
	s_nop 0
	v_pk_add_f32 v[42:43], v[120:121], v[120:121] op_sel:[0,1] op_sel_hi:[1,0]
	v_add_f32_e32 v44, v4, v5
	v_add_f32_e32 v46, v6, v7
	v_mov_b32_e32 v41, v0
	v_mov_b32_e32 v43, v1
	v_mov_b32_e32 v45, v2
	v_mov_b32_e32 v47, v3
	v_pk_add_f32 v[40:41], v[40:41], v[42:43]
	v_pk_add_f32 v[42:43], v[44:45], v[46:47]
	s_nop 0
	v_pk_add_f32 v[40:41], v[40:41], v[42:43]
	s_nop 0
	v_add_f32_e32 v30, v40, v41
	ds_bpermute_b32 v39, v32, v30
	s_waitcnt lgkmcnt(0)
	v_add_f32_e32 v30, v30, v39
	ds_bpermute_b32 v39, v33, v30
	s_waitcnt lgkmcnt(0)
	v_add_f32_e32 v30, v30, v39
	ds_bpermute_b32 v39, v34, v30
	s_waitcnt lgkmcnt(0)
	v_add_f32_e32 v30, v30, v39
	ds_bpermute_b32 v39, v35, v30
	s_waitcnt lgkmcnt(0)
	v_add_f32_e32 v30, v30, v39
	ds_bpermute_b32 v39, v36, v30
	s_waitcnt lgkmcnt(0)
	v_add_f32_e32 v30, v30, v39
	ds_bpermute_b32 v39, v37, v30
	s_waitcnt lgkmcnt(0)
	v_add_f32_e32 v39, v30, v39
	v_fmamk_f32 v15, v39, 0xba800000, v15
	v_fmamk_f32 v14, v39, 0xba800000, v14
	v_fmamk_f32 v13, v39, 0xba800000, v13
	v_fmac_f32_e32 v12, 0xba800000, v39
	v_pk_mul_f32 v[40:41], v[14:15], v[14:15]
	v_pk_mul_f32 v[42:43], v[12:13], v[12:13]
	v_fmamk_f32 v11, v39, 0xba800000, v11
	v_pk_mov_b32 v[44:45], v[42:43], v[40:41] op_sel:[1,0]
	v_mov_b32_e32 v43, v41
	v_fmamk_f32 v10, v39, 0xba800000, v10
	v_fmamk_f32 v9, v39, 0xba800000, v9
	v_fmac_f32_e32 v8, 0xba800000, v39
	v_pk_add_f32 v[40:41], v[44:45], v[42:43]
	v_pk_mul_f32 v[42:43], v[10:11], v[10:11]
	v_pk_mul_f32 v[44:45], v[8:9], v[8:9]
	v_fmac_f32_e32 v4, 0xba800000, v39
	v_pk_mov_b32 v[46:47], v[44:45], v[42:43] op_sel:[1,0]
	v_mov_b32_e32 v45, v43
	v_fmamk_f32 v6, v39, 0xba800000, v6
	v_fmamk_f32 v5, v39, 0xba800000, v5
	v_mul_f32_e32 v30, v4, v4
	v_pk_add_f32 v[42:43], v[46:47], v[44:45]
	v_fmamk_f32 v7, v39, 0xba800000, v7
	v_pk_fma_f32 v[44:45], v[4:5], v[4:5], v[30:31] op_sel_hi:[1,1,0]
	v_mul_f32_e32 v30, v6, v6
	v_pk_add_f32 v[40:41], v[40:41], v[40:41] op_sel_hi:[0,1]
	v_pk_add_f32 v[42:43], v[42:43], v[42:43] op_sel_hi:[0,1]
	v_pk_fma_f32 v[46:47], v[6:7], v[6:7], v[30:31] op_sel_hi:[1,1,0]
	v_fmamk_f32 v3, v39, 0xba800000, v3
	v_fmamk_f32 v2, v39, 0xba800000, v2
	v_fmamk_f32 v1, v39, 0xba800000, v1
	v_fmac_f32_e32 v0, 0xba800000, v39
	v_mul_f32_e32 v44, v0, v0
	v_mul_f32_e32 v46, v1, v1
	v_mul_f32_e32 v40, v2, v2
	v_mul_f32_e32 v42, v3, v3
	v_pk_add_f32 v[44:45], v[44:45], v[46:47]
	v_pk_add_f32 v[40:41], v[40:41], v[42:43]
	s_nop 0
	v_pk_add_f32 v[40:41], v[44:45], v[40:41]
	s_nop 0
	v_add_f32_e32 v30, v40, v41
	ds_bpermute_b32 v40, v32, v30
	s_waitcnt lgkmcnt(0)
	v_add_f32_e32 v30, v30, v40
	ds_bpermute_b32 v40, v33, v30
	s_waitcnt lgkmcnt(0)
	v_add_f32_e32 v30, v30, v40
	ds_bpermute_b32 v40, v34, v30
	s_waitcnt lgkmcnt(0)
	v_add_f32_e32 v30, v30, v40
	ds_bpermute_b32 v40, v35, v30
	s_waitcnt lgkmcnt(0)
	v_add_f32_e32 v30, v30, v40
	ds_bpermute_b32 v40, v36, v30
	s_waitcnt lgkmcnt(0)
	v_add_f32_e32 v30, v30, v40
	ds_bpermute_b32 v40, v37, v30
	s_waitcnt lgkmcnt(0)
	v_add_f32_e32 v30, v30, v40
	v_fmamk_f32 v30, v30, 0x3a800000, v38
	v_cmp_gt_f32_e64 s[0:1], s0, v30
	v_mul_f32_e32 v40, 0x4b800000, v30
	s_nop 0
	v_cndmask_b32_e64 v30, v30, v40, s[0:1]
	v_rsq_f32_e32 v30, v30
	s_nop 0
	v_mul_f32_e32 v40, 0x45800000, v30
	v_cndmask_b32_e64 v30, v30, v40, s[0:1]
	s_and_saveexec_b64 s[0:1], vcc
	s_cbranch_execz .LBB0_781
	v_mul_f32_e32 v40, 0x3a800000, v39
	v_mov_b32_e32 v41, v30
	global_store_dwordx2 v[24:25], v[40:41], off
	s_branch .LBB0_781

; DI int tidx() { int t = __builtin_amdgcn_workitem_id_x(); asm volatile("" : "+v"(t)); return t; }
; DI void phase_ln(const Params& p, const float* g, const float* bta, const float* sh, const float* sc, bool writex, int bid, int nb) {
;   const int tid = tidx(), lane = tid & 63, wid = tid >> 6;
;   for (int row = bid * 8 + wid; row < NTOK; row += nb * 8) {
;     float* xr = p.out + (size_t)row * DM; const int b = row >> 12;
;     f32x4 v[4]; float s = 0.f;
; #pragma unroll
;     for (int e = 0; e < 4; ++e) { v[e] = *(const f32x4*)(xr + e * 256 + lane * 4); s += (v[e][0] + v[e][1]) + (v[e][2] + v[e][3]); }
; #pragma unroll
;     for (int o = 32; o > 0; o >>= 1) s += __shfl_xor(s, o);
;     const float mu = s * (1.f / 1024.f); float q = 0.f;
; #pragma unroll
;     for (int e = 0; e < 4; ++e) { v[e] -= mu; q += (v[e][0] * v[e][0] + v[e][1] * v[e][1]) + (v[e][2] * v[e][2] + v[e][3] * v[e][3]); }
; #pragma unroll
;     for (int o = 32; o > 0; o >>= 1) q += __shfl_xor(q, o);
;     const float rstd = rsqrtf(q * (1.f / 1024.f) + 1e-5f);
;     if (!writex && lane == 0) { f32x2 ms = {mu, rstd}; *(f32x2*)(p.lnstat + (size_t)row * 2) = ms; }
; DI void run_phase(const Params& p, int ph, char* lds, int bid, int nb) {
;     ...
;     const float* nmod = p.mod + (size_t)(l + 1) * 8 * 6144;
;     if (bid == 0 && l == 0) for (int i = tidx(); i < 6144; i += 512) p.nmax[i] = 0u;
;     phase_ln(p, p.ln_mlp_g + l * 1024, p.ln_mlp_b + l * 1024, l == 0 ? nmod : nullptr, l == 0 ? nmod + 1024 : nullptr, l == 1, bid, nb);
.LBB0_1070:
	v_mov_b32_e32 v1, v206
	v_readlane_b32 s0, v255, 3
	v_ashrrev_i32_e32 v0, 6, v1
	v_readlane_b32 s1, v255, 4
	v_add_u32_e32 v31, s0, v0
	s_mov_b32 s0, 0x8000
	v_cmp_gt_i32_e32 vcc, s0, v31
	s_and_saveexec_b64 s[2:3], vcc
	s_cbranch_execz .LBB0_1075
	v_cmp_lt_i32_e64 s[0:1], v209, v208
	v_and_b32_e32 v6, 63, v1
	v_readlane_b32 s8, v252, 17
	v_cndmask_b32_e64 v1, v207, v209, s[0:1]
	v_lshlrev_b32_e32 v32, 2, v1
	v_xor_b32_e32 v1, 16, v207
	v_cmp_lt_i32_e64 s[0:1], v1, v208
	v_lshlrev_b32_e32 v2, 4, v6
	v_mov_b32_e32 v3, 0
	v_cndmask_b32_e64 v1, v207, v1, s[0:1]
	v_lshlrev_b32_e32 v33, 2, v1
	v_xor_b32_e32 v1, 8, v207
	v_cmp_lt_i32_e64 s[0:1], v1, v208
	v_readlane_b32 s16, v252, 25
	v_readlane_b32 s17, v252, 26
	v_cndmask_b32_e64 v1, v207, v1, s[0:1]
	v_lshlrev_b32_e32 v34, 2, v1
	v_xor_b32_e32 v1, 4, v207
	v_cmp_lt_i32_e64 s[0:1], v1, v208
	v_lshl_add_u64 v[4:5], s[16:17], 0, v[2:3]
	v_readlane_b32 s9, v252, 18
	v_cndmask_b32_e64 v1, v207, v1, s[0:1]
	v_lshlrev_b32_e32 v35, 2, v1
	v_xor_b32_e32 v1, 2, v207
	v_cmp_lt_i32_e64 s[0:1], v1, v208
	v_readlane_b32 s10, v252, 19
	v_readlane_b32 s11, v252, 20
	v_cndmask_b32_e64 v1, v207, v1, s[0:1]
	v_lshlrev_b32_e32 v36, 2, v1
	v_xor_b32_e32 v1, 1, v207
	v_cmp_lt_i32_e64 s[0:1], v1, v208
	v_readlane_b32 s12, v252, 21
	v_readlane_b32 s13, v252, 22
	v_cndmask_b32_e64 v1, v207, v1, s[0:1]
	s_mov_b64 s[0:1], 0x31000
	v_lshl_add_u64 v[20:21], v[4:5], 0, s[0:1]
	s_mov_b64 s[0:1], 0x30000
	v_lshl_add_u64 v[22:23], v[4:5], 0, s[0:1]
	v_readlane_b32 s0, v255, 3
	v_lshlrev_b32_e32 v37, 2, v1
	v_readlane_b32 s14, v252, 23
	v_readlane_b32 s15, v252, 24
	v_readlane_b32 s18, v252, 27
	v_readlane_b32 s19, v252, 28
	v_readlane_b32 s20, v252, 29
	v_readlane_b32 s21, v252, 30
	v_readlane_b32 s22, v252, 31
	v_readlane_b32 s23, v252, 32
	v_ashrrev_i32_e32 v1, 31, v0
	s_mov_b32 s6, s0
	s_ashr_i32 s7, s0, 31
	v_lshl_add_u64 v[0:1], v[0:1], 0, s[6:7]
	v_readlane_b32 s8, v252, 0
	v_readlane_b32 s1, v255, 4
	v_readlane_b32 s9, v252, 1
	v_lshlrev_b64 v[4:5], 12, v[0:1]
	v_writelane_b32 v255, s0, 3
	v_lshl_add_u64 v[24:25], v[0:1], 3, s[8:9]
	v_or_b32_e32 v4, v4, v2
	v_lshlrev_b64 v[0:1], 11, v[0:1]
	s_lshl_b32 s4, s38, 3
	v_lshl_add_u64 v[16:17], s[80:81], 0, v[2:3]
	v_lshl_add_u64 v[18:19], s[82:83], 0, v[2:3]
	v_writelane_b32 v255, s1, 4
	v_readlane_b32 s14, v252, 6
	v_readlane_b32 s15, v252, 7
	v_lshl_add_u64 v[2:3], s[84:85], 0, v[4:5]
	s_mov_b64 s[0:1], 0x800
	v_lshl_or_b32 v0, v6, 3, v0
	v_readlane_b32 s10, v252, 2
	v_readlane_b32 s11, v252, 3
	v_readlane_b32 s12, v252, 4
	v_readlane_b32 s13, v252, 5
	s_ashr_i32 s5, s4, 31
	v_lshl_add_u64 v[26:27], v[2:3], 0, s[0:1]
	v_lshl_add_u64 v[0:1], s[14:15], 0, v[0:1]
	s_mov_b64 s[0:1], 0x400
	v_cmp_eq_u32_e32 vcc, 0, v6
	s_lshl_b64 s[6:7], s[4:5], 3
	s_lshl_b64 s[8:9], s[4:5], 12
	v_lshl_add_u64 v[28:29], v[0:1], 0, s[0:1]
	s_lshl_b64 s[10:11], s[4:5], 11
	s_mov_b64 s[12:13], 0
	v_mov_b32_e32 v38, 0x3727c5ac
	v_readlane_b32 s16, v252, 8
	v_readlane_b32 s17, v252, 9
	v_readlane_b32 s18, v252, 10
	v_readlane_b32 s19, v252, 11
	v_readlane_b32 s20, v252, 12
	v_readlane_b32 s21, v252, 13
	v_readlane_b32 s22, v252, 14
	v_readlane_b32 s23, v252, 15
	global_load_dwordx4 v[52:55], v[16:17], off
	global_load_dwordx4 v[68:71], v[18:19], off
	global_load_dwordx4 v[56:59], v[16:17], off offset:1024
	global_load_dwordx4 v[72:75], v[18:19], off offset:1024
	global_load_dwordx4 v[60:63], v[16:17], off offset:2048
	global_load_dwordx4 v[76:79], v[18:19], off offset:2048
	global_load_dwordx4 v[64:67], v[16:17], off offset:3072
	global_load_dwordx4 v[80:83], v[18:19], off offset:3072
	global_load_dwordx4 v[124:127], v[26:27], off offset:-2048
	global_load_dwordx4 v[128:131], v[26:27], off offset:-1024
	global_load_dwordx4 v[132:135], v[26:27], off
	global_load_dwordx4 v[136:139], v[26:27], off offset:1024
	s_waitcnt vmcnt(0)
	s_branch .LBB0_1073

; DI void st4(bf16_t* p, float a, float b, float c, float d) { u32x2 w = {pk2(a, b), pk2(c, d)}; *(u32x2*)p = w; }
; DI void phase_ln(const Params& p, const float* g, const float* bta, const float* sh, const float* sc, bool writex, int bid, int nb) {
;     ...
;   for (int row = bid * 8 + wid; row < NTOK; row += nb * 8) {
;     float* xr = p.out + (size_t)row * DM; const int b = row >> 12;
;     f32x4 v[4]; float s = 0.f;
; #pragma unroll
;     for (int e = 0; e < 4; ++e) { v[e] = *(const f32x4*)(xr + e * 256 + lane * 4); s += (v[e][0] + v[e][1]) + (v[e][2] + v[e][3]); }
; #pragma unroll
;     for (int o = 32; o > 0; o >>= 1) s += __shfl_xor(s, o);
;     const float mu = s * (1.f / 1024.f); float q = 0.f;
; #pragma unroll
;     for (int e = 0; e < 4; ++e) { v[e] -= mu; q += (v[e][0] * v[e][0] + v[e][1] * v[e][1]) + (v[e][2] * v[e][2] + v[e][3] * v[e][3]); }
; #pragma unroll
;     for (int o = 32; o > 0; o >>= 1) q += __shfl_xor(q, o);
;     const float rstd = rsqrtf(q * (1.f / 1024.f) + 1e-5f);
;     if (!writex && lane == 0) { f32x2 ms = {mu, rstd}; *(f32x2*)(p.lnstat + (size_t)row * 2) = ms; }
; #pragma unroll
;     for (int e = 0; e < 4; ++e) { const int col = e * 256 + lane * 4;
;       const f32x4 y = v[e] * rstd * *(const f32x4*)(g + col) + *(const f32x4*)(bta + col);
;       if (writex) *(f32x4*)(xr + col) = y;
;       if (sh) { const f32x4 hv = y * (*(const f32x4*)(sc + b * 6144 + col) + 1.f) + *(const f32x4*)(sh + b * 6144 + col); st4(p.H + (size_t)row * DM + col, hv[0], hv[1], hv[2], hv[3]); } }
.LBB0_1073:
	s_waitcnt vmcnt(5)
	v_mov_b64_e32 v[12:13], v[124:125]
	v_mov_b64_e32 v[14:15], v[126:127]
	v_mov_b64_e32 v[8:9], v[128:129]
	v_mov_b64_e32 v[10:11], v[130:131]
	v_mov_b64_e32 v[4:5], v[132:133]
	v_mov_b64_e32 v[6:7], v[134:135]
	v_mov_b64_e32 v[0:1], v[136:137]
	v_mov_b64_e32 v[2:3], v[138:139]
	v_ashrrev_i32_e32 v116, 12, v31
	v_mul_i32_i24_e32 v116, 0x1800, v116
	v_ashrrev_i32_e32 v117, 31, v116
	v_lshlrev_b64 v[116:117], 2, v[116:117]
	v_lshl_add_u64 v[118:119], v[20:21], 0, v[116:117]
	v_lshl_add_u64 v[116:117], v[22:23], 0, v[116:117]
	global_load_dwordx4 v[84:87], v[118:119], off
	global_load_dwordx4 v[100:103], v[116:117], off
	global_load_dwordx4 v[88:91], v[118:119], off offset:1024
	global_load_dwordx4 v[104:107], v[116:117], off offset:1024
	global_load_dwordx4 v[92:95], v[118:119], off offset:2048
	global_load_dwordx4 v[108:111], v[116:117], off offset:2048
	global_load_dwordx4 v[96:99], v[118:119], off offset:3072
	global_load_dwordx4 v[112:115], v[116:117], off offset:3072
	v_add_u32_e32 v140, s4, v31
	s_movk_i32 s100, 0x7fff
	v_cmp_ge_i32_e64 s[98:99], s100, v140
	v_lshl_add_u64 v[142:143], v[26:27], 0, s[8:9]
	s_nop 1
	v_cndmask_b32_e64 v142, v26, v142, s[98:99]
	v_cndmask_b32_e64 v143, v27, v143, s[98:99]
	global_load_dwordx4 v[124:127], v[142:143], off offset:-2048
	global_load_dwordx4 v[128:131], v[142:143], off offset:-1024
	global_load_dwordx4 v[132:135], v[142:143], off
	global_load_dwordx4 v[136:139], v[142:143], off offset:1024
	s_mov_b32 s0, 0x800000
	v_mov_b32_e32 v120, v13
	v_mov_b32_e32 v121, v14
	v_mov_b32_e32 v122, v12
	v_mov_b32_e32 v123, v15
	v_pk_add_f32 v[120:121], v[120:121], v[122:123]
	v_mov_b32_e32 v122, v8
	v_add_f32_e32 v120, v120, v121
	v_add_f32_e32 v40, 0, v120
	v_mov_b32_e32 v120, v9
	v_mov_b32_e32 v121, v10
	v_mov_b32_e32 v123, v11
	v_pk_add_f32 v[120:121], v[120:121], v[122:123]
	s_nop 0
	v_pk_add_f32 v[42:43], v[120:121], v[120:121] op_sel:[0,1] op_sel_hi:[1,0]
	v_add_f32_e32 v44, v4, v5
	v_add_f32_e32 v46, v6, v7
	v_mov_b32_e32 v41, v0
	v_mov_b32_e32 v43, v1
	v_mov_b32_e32 v45, v2
	v_mov_b32_e32 v47, v3
	v_pk_add_f32 v[40:41], v[40:41], v[42:43]
	v_pk_add_f32 v[42:43], v[44:45], v[46:47]
	s_nop 0
	v_pk_add_f32 v[40:41], v[40:41], v[42:43]
	s_nop 0
	v_add_f32_e32 v30, v40, v41
	ds_bpermute_b32 v39, v32, v30
	s_waitcnt lgkmcnt(0)
	v_add_f32_e32 v30, v30, v39
	ds_bpermute_b32 v39, v33, v30
	s_waitcnt lgkmcnt(0)
	v_add_f32_e32 v30, v30, v39
	ds_bpermute_b32 v39, v34, v30
	s_waitcnt lgkmcnt(0)
	v_add_f32_e32 v30, v30, v39
	ds_bpermute_b32 v39, v35, v30
	s_waitcnt lgkmcnt(0)
	v_add_f32_e32 v30, v30, v39
	ds_bpermute_b32 v39, v36, v30
	s_waitcnt lgkmcnt(0)
	v_add_f32_e32 v30, v30, v39
	ds_bpermute_b32 v39, v37, v30
	s_waitcnt lgkmcnt(0)
	v_add_f32_e32 v39, v30, v39
	v_fmamk_f32 v15, v39, 0xba800000, v15
	v_fmamk_f32 v14, v39, 0xba800000, v14
	v_fmamk_f32 v13, v39, 0xba800000, v13
	v_fmac_f32_e32 v12, 0xba800000, v39
	v_pk_mul_f32 v[40:41], v[14:15], v[14:15]
	v_pk_mul_f32 v[42:43], v[12:13], v[12:13]
	v_fmamk_f32 v11, v39, 0xba800000, v11
	v_pk_mov_b32 v[44:45], v[42:43], v[40:41] op_sel:[1,0]
	v_mov_b32_e32 v43, v41
	v_fmamk_f32 v10, v39, 0xba800000, v10
	v_fmamk_f32 v9, v39, 0xba800000, v9
	v_fmac_f32_e32 v8, 0xba800000, v39
	v_pk_add_f32 v[40:41], v[44:45], v[42:43]
	v_pk_mul_f32 v[42:43], v[10:11], v[10:11]
	v_pk_mul_f32 v[44:45], v[8:9], v[8:9]
	v_fmac_f32_e32 v4, 0xba800000, v39
	v_pk_mov_b32 v[46:47], v[44:45], v[42:43] op_sel:[1,0]
	v_mov_b32_e32 v45, v43
	v_fmamk_f32 v6, v39, 0xba800000, v6
	v_fmamk_f32 v5, v39, 0xba800000, v5
	v_mul_f32_e32 v30, v4, v4
	v_pk_add_f32 v[42:43], v[46:47], v[44:45]
	v_fmamk_f32 v7, v39, 0xba800000, v7
	v_pk_fma_f32 v[44:45], v[4:5], v[4:5], v[30:31] op_sel_hi:[1,1,0]
	v_mul_f32_e32 v30, v6, v6
	v_pk_add_f32 v[40:41], v[40:41], v[40:41] op_sel_hi:[0,1]
	v_pk_add_f32 v[42:43], v[42:43], v[42:43] op_sel_hi:[0,1]
	v_pk_fma_f32 v[46:47], v[6:7], v[6:7], v[30:31] op_sel_hi:[1,1,0]
	v_fmamk_f32 v3, v39, 0xba800000, v3
	v_fmamk_f32 v2, v39, 0xba800000, v2
	v_fmamk_f32 v1, v39, 0xba800000, v1
	v_fmac_f32_e32 v0, 0xba800000, v39
	v_mul_f32_e32 v44, v0, v0
	v_mul_f32_e32 v46, v1, v1
	v_mul_f32_e32 v40, v2, v2
	v_mul_f32_e32 v42, v3, v3
	v_pk_add_f32 v[44:45], v[44:45], v[46:47]
	v_pk_add_f32 v[40:41], v[40:41], v[42:43]
	s_nop 0
	v_pk_add_f32 v[40:41], v[44:45], v[40:41]
	s_nop 0
	v_add_f32_e32 v30, v40, v41
	ds_bpermute_b32 v40, v32, v30
	s_waitcnt lgkmcnt(0)
	v_add_f32_e32 v30, v30, v40
	ds_bpermute_b32 v40, v33, v30
	s_waitcnt lgkmcnt(0)
	v_add_f32_e32 v30, v30, v40
	ds_bpermute_b32 v40, v34, v30
	s_waitcnt lgkmcnt(0)
	v_add_f32_e32 v30, v30, v40
	ds_bpermute_b32 v40, v35, v30
	s_waitcnt lgkmcnt(0)
	v_add_f32_e32 v30, v30, v40
	ds_bpermute_b32 v40, v36, v30
	s_waitcnt lgkmcnt(0)
	v_add_f32_e32 v30, v30, v40
	ds_bpermute_b32 v40, v37, v30
	s_waitcnt lgkmcnt(0)
	v_add_f32_e32 v30, v30, v40
	v_fmamk_f32 v30, v30, 0x3a800000, v38
	v_cmp_gt_f32_e64 s[0:1], s0, v30
	v_mul_f32_e32 v40, 0x4b800000, v30
	s_nop 0
	v_cndmask_b32_e64 v30, v30, v40, s[0:1]
	v_rsq_f32_e32 v30, v30
	s_nop 0
	v_mul_f32_e32 v40, 0x45800000, v30
	v_cndmask_b32_e64 v30, v30, v40, s[0:1]
	s_and_saveexec_b64 s[0:1], vcc
	s_cbranch_execz .LBB0_1072
	v_mul_f32_e32 v40, 0x3a800000, v39
	v_mov_b32_e32 v41, v30
	global_store_dwordx2 v[24:25], v[40:41], off
	s_branch .LBB0_1072

; DI int tidx() { int t = __builtin_amdgcn_workitem_id_x(); asm volatile("" : "+v"(t)); return t; }
; DI void phase_ln(const Params& p, const float* g, const float* bta, const float* sh, const float* sc, bool writex, int bid, int nb) {
;   const int tid = tidx(), lane = tid & 63, wid = tid >> 6;
;   for (int row = bid * 8 + wid; row < NTOK; row += nb * 8) {
;     float* xr = p.out + (size_t)row * DM; const int b = row >> 12;
;     f32x4 v[4]; float s = 0.f;
; #pragma unroll
;     for (int e = 0; e < 4; ++e) { v[e] = *(const f32x4*)(xr + e * 256 + lane * 4); s += (v[e][0] + v[e][1]) + (v[e][2] + v[e][3]); }
; #pragma unroll
;     for (int o = 32; o > 0; o >>= 1) s += __shfl_xor(s, o);
;     const float mu = s * (1.f / 1024.f); float q = 0.f;
; #pragma unroll
;     for (int e = 0; e < 4; ++e) { v[e] -= mu; q += (v[e][0] * v[e][0] + v[e][1] * v[e][1]) + (v[e][2] * v[e][2] + v[e][3] * v[e][3]); }
; #pragma unroll
;     for (int o = 32; o > 0; o >>= 1) q += __shfl_xor(q, o);
;     const float rstd = rsqrtf(q * (1.f / 1024.f) + 1e-5f);
;     if (!writex && lane == 0) { f32x2 ms = {mu, rstd}; *(f32x2*)(p.lnstat + (size_t)row * 2) = ms; }
.LBB0_1828:
	s_or_b64 exec, exec, s[0:1]
	v_mov_b32_e32 v1, v206
	s_waitcnt lgkmcnt(0)
	s_barrier
	s_mov_b32 s0, 0x8000
	v_ashrrev_i32_e32 v0, 6, v1
	v_add_u32_e32 v43, s94, v0
	v_cmp_gt_i32_e32 vcc, s0, v43
	s_and_saveexec_b64 s[2:3], vcc
	s_cbranch_execz .LBB0_1833
	v_readlane_b32 s4, v252, 60
	v_readlane_b32 s12, v251, 4
	v_readlane_b32 s13, v251, 5
	v_readlane_b32 s14, v251, 6
	v_readlane_b32 s15, v251, 7
	v_readlane_b32 s16, v251, 8
	v_readlane_b32 s17, v251, 9
	v_readlane_b32 s18, v251, 10
	v_readlane_b32 s19, v251, 11
	s_mov_b64 s[12:13], s[16:17]
	v_readlane_b32 s6, v252, 62
	s_mov_b64 s[14:15], s[18:19]
	v_readlane_b32 s7, v252, 63
	s_add_u32 s6, s14, 0x1000
	v_readlane_b32 s8, v251, 0
	s_addc_u32 s7, s15, 0
	v_readlane_b32 s0, v251, 16
	v_readlane_b32 s9, v251, 1
	s_add_u32 s8, s12, 0x1000
	v_readlane_b32 s1, v251, 17
	s_addc_u32 s9, s13, 0
	s_lshl_b32 s4, s0, 3
	v_cmp_lt_i32_e64 s[0:1], v209, v208
	v_and_b32_e32 v6, 63, v1
	v_lshlrev_b32_e32 v2, 4, v6
	v_cndmask_b32_e64 v1, v207, v209, s[0:1]
	v_lshlrev_b32_e32 v44, 2, v1
	v_xor_b32_e32 v1, 16, v207
	v_cmp_lt_i32_e64 s[0:1], v1, v208
	v_mov_b32_e32 v3, 0
	v_or_b32_e32 v4, 0x400, v2
	v_cndmask_b32_e64 v1, v207, v1, s[0:1]
	v_lshlrev_b32_e32 v45, 2, v1
	v_xor_b32_e32 v1, 8, v207
	v_cmp_lt_i32_e64 s[0:1], v1, v208
	v_mov_b32_e32 v5, v3
	v_lshl_add_u64 v[20:21], s[8:9], 0, v[4:5]
	v_cndmask_b32_e64 v1, v207, v1, s[0:1]
	v_lshlrev_b32_e32 v46, 2, v1
	v_xor_b32_e32 v1, 4, v207
	v_cmp_lt_i32_e64 s[0:1], v1, v208
	v_lshl_add_u64 v[22:23], s[6:7], 0, v[4:5]
	v_or_b32_e32 v4, 0x800, v2
	v_cndmask_b32_e64 v1, v207, v1, s[0:1]
	v_lshlrev_b32_e32 v47, 2, v1
	v_xor_b32_e32 v1, 2, v207
	v_cmp_lt_i32_e64 s[0:1], v1, v208
	v_readlane_b32 s10, v251, 2
	v_readlane_b32 s11, v251, 3
	v_cndmask_b32_e64 v1, v207, v1, s[0:1]
	v_lshlrev_b32_e32 v48, 2, v1
	v_xor_b32_e32 v1, 1, v207
	v_lshl_add_u64 v[24:25], s[8:9], 0, v[4:5]
	v_lshl_add_u64 v[26:27], s[6:7], 0, v[4:5]
	v_or_b32_e32 v4, 0xc00, v2
	v_cmp_lt_i32_e64 s[0:1], v1, v208
	v_lshl_add_u64 v[16:17], s[8:9], 0, v[2:3]
	v_lshl_add_u64 v[28:29], s[8:9], 0, v[4:5]
	v_readlane_b32 s8, v252, 17
	v_cndmask_b32_e64 v1, v207, v1, s[0:1]
	v_readlane_b32 s9, v252, 18
	v_readlane_b32 s10, v252, 19
	v_readlane_b32 s11, v252, 20
	v_readlane_b32 s12, v252, 21
	v_readlane_b32 s13, v252, 22
	v_readlane_b32 s14, v252, 23
	v_readlane_b32 s15, v252, 24
	v_readlane_b32 s16, v252, 25
	v_readlane_b32 s17, v252, 26
	v_readlane_b32 s18, v252, 27
	v_readlane_b32 s19, v252, 28
	v_readlane_b32 s20, v252, 29
	v_readlane_b32 s21, v252, 30
	v_readlane_b32 s22, v252, 31
	v_readlane_b32 s23, v252, 32
	v_lshlrev_b32_e32 v49, 2, v1
	v_lshl_add_u64 v[30:31], s[6:7], 0, v[4:5]
	v_lshl_add_u64 v[4:5], s[16:17], 0, v[2:3]
	s_mov_b64 s[0:1], 0x34000
	v_ashrrev_i32_e32 v1, 31, v0
	s_ashr_i32 s95, s94, 31
	v_readlane_b32 s8, v252, 0
	v_lshl_add_u64 v[32:33], v[4:5], 0, s[0:1]
	s_mov_b64 s[0:1], 0x33000
	v_lshl_add_u64 v[0:1], v[0:1], 0, s[94:95]
	v_readlane_b32 s16, v252, 8
	v_readlane_b32 s17, v252, 9
	v_readlane_b32 s18, v252, 10
	v_readlane_b32 s19, v252, 11
	v_readlane_b32 s20, v252, 12
	v_readlane_b32 s21, v252, 13
	v_readlane_b32 s22, v252, 14
	v_readlane_b32 s23, v252, 15
	v_lshl_add_u64 v[34:35], v[4:5], 0, s[0:1]
	v_readlane_b32 s9, v252, 1
	v_lshlrev_b64 v[4:5], 12, v[0:1]
	v_readlane_b32 s16, v251, 19
	v_lshl_add_u64 v[36:37], v[0:1], 3, s[8:9]
	v_or_b32_e32 v4, v4, v2
	v_readlane_b32 s24, v251, 27
	v_readlane_b32 s25, v251, 28
	v_lshlrev_b64 v[0:1], 11, v[0:1]
	v_readlane_b32 s5, v252, 61
	v_lshl_add_u64 v[18:19], s[6:7], 0, v[2:3]
	v_readlane_b32 s14, v252, 6
	v_readlane_b32 s15, v252, 7
	v_lshl_add_u64 v[2:3], s[24:25], 0, v[4:5]
	s_mov_b64 s[0:1], 0x800
	v_lshl_or_b32 v0, v6, 3, v0
	v_readlane_b32 s10, v252, 2
	v_readlane_b32 s11, v252, 3
	v_readlane_b32 s12, v252, 4
	v_readlane_b32 s13, v252, 5
	s_ashr_i32 s5, s4, 31
	v_lshl_add_u64 v[38:39], v[2:3], 0, s[0:1]
	v_lshl_add_u64 v[0:1], s[14:15], 0, v[0:1]
	s_mov_b64 s[0:1], 0x400
	v_cmp_eq_u32_e32 vcc, 0, v6
	s_lshl_b64 s[6:7], s[4:5], 3
	s_lshl_b64 s[8:9], s[4:5], 12
	v_lshl_add_u64 v[40:41], v[0:1], 0, s[0:1]
	s_lshl_b64 s[10:11], s[4:5], 11
	s_mov_b64 s[12:13], 0
	v_mov_b32_e32 v50, 0x3727c5ac
	s_mov_b32 s5, 0x800000
	s_movk_i32 s14, 0x7fff
	v_readlane_b32 s17, v251, 20
	v_readlane_b32 s18, v251, 21
	v_readlane_b32 s19, v251, 22
	v_readlane_b32 s20, v251, 23
	v_readlane_b32 s21, v251, 24
	v_readlane_b32 s22, v251, 25
	v_readlane_b32 s23, v251, 26
	v_readlane_b32 s26, v251, 29
	v_readlane_b32 s27, v251, 30
	v_readlane_b32 s28, v251, 31
	v_readlane_b32 s29, v251, 32
	v_readlane_b32 s30, v251, 33
	v_readlane_b32 s31, v251, 34
	global_load_dwordx4 v[72:75], v[16:17], off
	global_load_dwordx4 v[88:91], v[18:19], off
	global_load_dwordx4 v[76:79], v[20:21], off
	global_load_dwordx4 v[92:95], v[22:23], off
	global_load_dwordx4 v[80:83], v[24:25], off
	global_load_dwordx4 v[96:99], v[26:27], off
	global_load_dwordx4 v[84:87], v[28:29], off
	global_load_dwordx4 v[100:103], v[30:31], off
	global_load_dwordx4 v[136:139], v[38:39], off offset:-2048
	global_load_dwordx4 v[140:143], v[38:39], off offset:-1024
	global_load_dwordx4 v[144:147], v[38:39], off
	global_load_dwordx4 v[148:151], v[38:39], off offset:1024
	s_waitcnt vmcnt(0)
	s_branch .LBB0_1831

; DI void st4(bf16_t* p, float a, float b, float c, float d) { u32x2 w = {pk2(a, b), pk2(c, d)}; *(u32x2*)p = w; }
; DI void phase_ln(const Params& p, const float* g, const float* bta, const float* sh, const float* sc, bool writex, int bid, int nb) {
;     ...
;   for (int row = bid * 8 + wid; row < NTOK; row += nb * 8) {
;     float* xr = p.out + (size_t)row * DM; const int b = row >> 12;
;     f32x4 v[4]; float s = 0.f;
; #pragma unroll
;     for (int e = 0; e < 4; ++e) { v[e] = *(const f32x4*)(xr + e * 256 + lane * 4); s += (v[e][0] + v[e][1]) + (v[e][2] + v[e][3]); }
; #pragma unroll
;     for (int o = 32; o > 0; o >>= 1) s += __shfl_xor(s, o);
;     const float mu = s * (1.f / 1024.f); float q = 0.f;
; #pragma unroll
;     for (int e = 0; e < 4; ++e) { v[e] -= mu; q += (v[e][0] * v[e][0] + v[e][1] * v[e][1]) + (v[e][2] * v[e][2] + v[e][3] * v[e][3]); }
; #pragma unroll
;     for (int o = 32; o > 0; o >>= 1) q += __shfl_xor(q, o);
;     const float rstd = rsqrtf(q * (1.f / 1024.f) + 1e-5f);
;     if (!writex && lane == 0) { f32x2 ms = {mu, rstd}; *(f32x2*)(p.lnstat + (size_t)row * 2) = ms; }
; #pragma unroll
;     for (int e = 0; e < 4; ++e) { const int col = e * 256 + lane * 4;
;       const f32x4 y = v[e] * rstd * *(const f32x4*)(g + col) + *(const f32x4*)(bta + col);
;       if (writex) *(f32x4*)(xr + col) = y;
;       if (sh) { const f32x4 hv = y * (*(const f32x4*)(sc + b * 6144 + col) + 1.f) + *(const f32x4*)(sh + b * 6144 + col); st4(p.H + (size_t)row * DM + col, hv[0], hv[1], hv[2], hv[3]); } }
.LBB0_1831:
	s_waitcnt vmcnt(5)
	v_mov_b64_e32 v[12:13], v[136:137]
	v_mov_b64_e32 v[14:15], v[138:139]
	v_mov_b64_e32 v[8:9], v[140:141]
	v_mov_b64_e32 v[10:11], v[142:143]
	v_mov_b64_e32 v[4:5], v[144:145]
	v_mov_b64_e32 v[6:7], v[146:147]
	v_mov_b64_e32 v[0:1], v[148:149]
	v_mov_b64_e32 v[2:3], v[150:151]
	v_ashrrev_i32_e32 v156, 12, v43
	v_mul_i32_i24_e32 v156, 0x1800, v156
	v_ashrrev_i32_e32 v157, 31, v156
	v_lshlrev_b64 v[156:157], 2, v[156:157]
	v_lshl_add_u64 v[158:159], v[32:33], 0, v[156:157]
	v_lshl_add_u64 v[156:157], v[34:35], 0, v[156:157]
	global_load_dwordx4 v[104:107], v[158:159], off
	global_load_dwordx4 v[120:123], v[156:157], off
	global_load_dwordx4 v[108:111], v[158:159], off offset:1024
	global_load_dwordx4 v[124:127], v[156:157], off offset:1024
	global_load_dwordx4 v[112:115], v[158:159], off offset:2048
	global_load_dwordx4 v[128:131], v[156:157], off offset:2048
	global_load_dwordx4 v[116:119], v[158:159], off offset:3072
	global_load_dwordx4 v[132:135], v[156:157], off offset:3072
	v_add_u32_e32 v160, s4, v43
	v_cmp_ge_i32_e64 s[98:99], s14, v160
	v_lshl_add_u64 v[162:163], v[38:39], 0, s[8:9]
	s_nop 1
	v_cndmask_b32_e64 v162, v38, v162, s[98:99]
	v_cndmask_b32_e64 v163, v39, v163, s[98:99]
	global_load_dwordx4 v[136:139], v[162:163], off offset:-2048
	global_load_dwordx4 v[140:143], v[162:163], off offset:-1024
	global_load_dwordx4 v[144:147], v[162:163], off
	global_load_dwordx4 v[148:151], v[162:163], off offset:1024
	v_mov_b32_e32 v52, v13
	v_mov_b32_e32 v53, v14
	v_mov_b32_e32 v54, v12
	v_mov_b32_e32 v55, v15
	v_mov_b32_e32 v56, v9
	v_mov_b32_e32 v57, v10
	v_mov_b32_e32 v58, v8
	v_mov_b32_e32 v59, v11
	v_pk_add_f32 v[52:53], v[52:53], v[54:55]
	v_pk_add_f32 v[54:55], v[56:57], v[58:59]
	v_add_f32_e32 v42, v52, v53
	v_pk_add_f32 v[52:53], v[54:55], v[54:55] op_sel:[0,1] op_sel_hi:[1,0]
	v_add_f32_e32 v60, v4, v5
	v_add_f32_e32 v62, v6, v7
	v_mov_b32_e32 v65, v0
	v_mov_b32_e32 v61, v2
	v_mov_b32_e32 v63, v3
	v_add_f32_e32 v64, 0, v42
	v_mov_b32_e32 v53, v1
	v_pk_add_f32 v[56:57], v[60:61], v[62:63]
	v_pk_add_f32 v[52:53], v[64:65], v[52:53]
	s_nop 0
	v_pk_add_f32 v[52:53], v[52:53], v[56:57]
	s_nop 0
	v_add_f32_e32 v42, v52, v53
	ds_bpermute_b32 v51, v44, v42
	s_waitcnt lgkmcnt(0)
	v_add_f32_e32 v42, v42, v51
	ds_bpermute_b32 v51, v45, v42
	s_waitcnt lgkmcnt(0)
	v_add_f32_e32 v42, v42, v51
	ds_bpermute_b32 v51, v46, v42
	s_waitcnt lgkmcnt(0)
	v_add_f32_e32 v42, v42, v51
	ds_bpermute_b32 v51, v47, v42
	s_waitcnt lgkmcnt(0)
	v_add_f32_e32 v42, v42, v51
	ds_bpermute_b32 v51, v48, v42
	s_waitcnt lgkmcnt(0)
	v_add_f32_e32 v42, v42, v51
	ds_bpermute_b32 v51, v49, v42
	s_waitcnt lgkmcnt(0)
	v_add_f32_e32 v51, v42, v51
	v_fmamk_f32 v15, v51, 0xba800000, v15
	v_fmamk_f32 v14, v51, 0xba800000, v14
	v_fmamk_f32 v13, v51, 0xba800000, v13
	v_fmac_f32_e32 v12, 0xba800000, v51
	v_fmamk_f32 v11, v51, 0xba800000, v11
	v_fmamk_f32 v10, v51, 0xba800000, v10
	v_fmamk_f32 v9, v51, 0xba800000, v9
	v_fmac_f32_e32 v8, 0xba800000, v51
	v_pk_mul_f32 v[52:53], v[14:15], v[14:15]
	v_pk_mul_f32 v[54:55], v[12:13], v[12:13]
	v_pk_mul_f32 v[56:57], v[10:11], v[10:11]
	v_pk_mul_f32 v[58:59], v[8:9], v[8:9]
	v_fmamk_f32 v6, v51, 0xba800000, v6
	v_fmac_f32_e32 v4, 0xba800000, v51
	v_pk_mov_b32 v[62:63], v[54:55], v[52:53] op_sel:[1,0]
	v_mov_b32_e32 v55, v53
	v_pk_mov_b32 v[52:53], v[58:59], v[56:57] op_sel:[1,0]
	v_mov_b32_e32 v59, v57
	v_fmamk_f32 v7, v51, 0xba800000, v7
	v_fmamk_f32 v5, v51, 0xba800000, v5
	v_mul_f32_e32 v42, v4, v4
	v_mul_f32_e32 v60, v6, v6
	v_pk_add_f32 v[54:55], v[62:63], v[54:55]
	v_pk_add_f32 v[52:53], v[52:53], v[58:59]
	v_fmamk_f32 v3, v51, 0xba800000, v3
	v_fmamk_f32 v2, v51, 0xba800000, v2
	v_fmamk_f32 v1, v51, 0xba800000, v1
	v_fmac_f32_e32 v0, 0xba800000, v51
	v_pk_fma_f32 v[56:57], v[4:5], v[4:5], v[42:43] op_sel_hi:[1,1,0]
	v_pk_fma_f32 v[60:61], v[6:7], v[6:7], v[60:61] op_sel_hi:[1,1,0]
	v_pk_add_f32 v[54:55], v[54:55], v[54:55] op_sel_hi:[0,1]
	v_pk_add_f32 v[52:53], v[52:53], v[52:53] op_sel_hi:[0,1]
	v_mul_f32_e32 v56, v0, v0
	v_mul_f32_e32 v60, v1, v1
	v_mul_f32_e32 v54, v2, v2
	v_mul_f32_e32 v52, v3, v3
	v_pk_add_f32 v[56:57], v[56:57], v[60:61]
	v_pk_add_f32 v[52:53], v[54:55], v[52:53]
	s_nop 0
	v_pk_add_f32 v[52:53], v[56:57], v[52:53]
	s_nop 0
	v_add_f32_e32 v42, v52, v53
	ds_bpermute_b32 v52, v44, v42
	s_waitcnt lgkmcnt(0)
	v_add_f32_e32 v42, v42, v52
	ds_bpermute_b32 v52, v45, v42
	s_waitcnt lgkmcnt(0)
	v_add_f32_e32 v42, v42, v52
	ds_bpermute_b32 v52, v46, v42
	s_waitcnt lgkmcnt(0)
	v_add_f32_e32 v42, v42, v52
	ds_bpermute_b32 v52, v47, v42
	s_waitcnt lgkmcnt(0)
	v_add_f32_e32 v42, v42, v52
	ds_bpermute_b32 v52, v48, v42
	s_waitcnt lgkmcnt(0)
	v_add_f32_e32 v42, v42, v52
	ds_bpermute_b32 v52, v49, v42
	s_waitcnt lgkmcnt(0)
	v_add_f32_e32 v42, v42, v52
	v_fmamk_f32 v42, v42, 0x3a800000, v50
	v_mul_f32_e32 v52, 0x4b800000, v42
	v_cmp_gt_f32_e64 s[0:1], s5, v42
	s_nop 1
	v_cndmask_b32_e64 v42, v42, v52, s[0:1]
	v_rsq_f32_e32 v42, v42
	s_nop 0
	v_mul_f32_e32 v52, 0x45800000, v42
	v_cndmask_b32_e64 v42, v42, v52, s[0:1]
	s_and_saveexec_b64 s[0:1], vcc
	s_cbranch_execz .LBB0_1830
	v_mul_f32_e32 v52, 0x3a800000, v51
	v_mov_b32_e32 v53, v42
	global_store_dwordx2 v[36:37], v[52:53], off
	s_branch .LBB0_1830
